# HG lower-bound table staged once per workgroup (without conversion-phase change)
# baseline (speedup 1.0000x reference)
;     __device__ __forceinline__ const float* in(int i) const { return (const float*)(const __attribute__((address_space(1))) float*)ld(i); }
; __device__ __forceinline__ void lds_barrier() { asm volatile("s_waitcnt lgkmcnt(0)" ::: "memory"); __builtin_amdgcn_s_barrier(); asm volatile("" ::: "memory"); }
; __device__ __forceinline__ void hg_item_C(const Params& p, int l, int seg, int h, LAS float* sm, int tid, int lane, int wave) {
;     ...
;     const float gn1 = p.in(24)[l * 256 + h * 64 + lane];
;     lds_barrier();
;     if (tid < 128) {
;         const float* lg = p.in(23) + h * 128 + tid;
;         const float x0 = lg[0], x1 = lg[512], x2 = lg[1024], x3 = lg[1536];
;         const float m = fmaxf(fmaxf(x0, x1), fmaxf(x2, x3));
;         const float e0 = __expf(x0 - m), e1 = __expf(x1 - m), e2 = __expf(x2 - m), e3 = __expf(x3 - m);
;         const float inv = 1.0f / (e0 + e1 + e2 + e3);
;         float lb = 0.f;
;         if (l >= 1) lb += e1; if (l >= 2) lb += e2; if (l >= 3) lb += e3;
;         sm[L_LB2 + tid] = lb * inv;
;     }
.LBB0_409:
	s_and_b64 vcc, exec, s[0:1]
	s_cbranch_vccz .LBB0_447
	v_readlane_b32 s0, v253, 59
	s_and_b32 s11, s57, 3
	s_lshl_b32 s10, s11, 6
	v_mov_b32_e32 v0, s0
	ds_read_b64 v[2:3], v0
	v_readlane_b32 s0, v255, 12
	s_or_b32 s4, s10, s0
	v_or_b32_e32 v0, s4, v56
	v_lshlrev_b32_e32 v0, 2, v0
	s_waitcnt lgkmcnt(0)
	v_readfirstlane_b32 s0, v2
	v_readfirstlane_b32 s1, v3
	s_nop 4
	global_load_dword v48, v0, s[0:1]
	v_readlane_b32 s0, v253, 35
	s_nop 1
	v_mov_b32_e32 v0, s0
	ds_read_b64 v[2:3], v0
	s_waitcnt lgkmcnt(0)
	s_barrier
	s_movk_i32 s0, 0x80
	s_waitcnt lgkmcnt(0)
	v_readfirstlane_b32 s4, v2
	v_readfirstlane_b32 s5, v3
	v_cmp_gt_i32_e32 vcc, s0, v54
	s_cmpk_gt_u32 s57, 0x3ff
	s_cbranch_scc1 .Lmy_hgc_staged
	s_and_saveexec_b64 s[0:1], vcc
	s_cbranch_execz .LBB0_412
	v_readlane_b32 s2, v253, 60
	s_lshl_b32 s8, s11, 9
	v_ashrrev_i32_e32 v55, 31, v54
	v_mov_b32_e32 v0, s2
	ds_read_b64 v[2:3], v0
	s_movk_i32 s2, 0x1000
	v_readlane_b32 s6, v255, 16
	v_readlane_b32 s7, v255, 17
	s_waitcnt lgkmcnt(0)
	v_readfirstlane_b32 s9, v2
	v_readfirstlane_b32 s12, v3
	s_add_u32 s8, s9, s8
	s_addc_u32 s9, s12, 0
	v_lshl_add_u64 v[2:3], v[54:55], 2, s[8:9]
	v_add_co_u32_e32 v4, vcc, s2, v2
	s_nop 1
	v_addc_co_u32_e32 v5, vcc, 0, v3, vcc
	global_load_dword v0, v[4:5], off offset:2048
	s_nop 0
	global_load_dword v4, v[4:5], off
	s_nop 0
	global_load_dword v5, v[2:3], off
	s_nop 0
	global_load_dword v2, v[2:3], off offset:2048
	v_lshl_add_u32 v3, v54, 2, 0
	s_waitcnt vmcnt(0)
	v_max_f32_e32 v6, v0, v0
	s_waitcnt vmcnt(2)
	v_max_f32_e32 v7, v4, v4
	v_max_f32_e32 v6, v7, v6
	s_waitcnt vmcnt(0)
	v_max3_f32 v6, v5, v2, v6
	v_sub_f32_e32 v5, v5, v6
	v_sub_f32_e32 v2, v2, v6
	v_sub_f32_e32 v4, v4, v6
	v_mul_f32_e32 v5, 0x3fb8aa3b, v5
	v_mul_f32_e32 v2, 0x3fb8aa3b, v2
	v_sub_f32_e32 v0, v0, v6
	v_mul_f32_e32 v4, 0x3fb8aa3b, v4
	v_exp_f32_e32 v5, v5
	v_exp_f32_e32 v2, v2
	v_mul_f32_e32 v0, 0x3fb8aa3b, v0
	v_exp_f32_e32 v4, v4
	v_exp_f32_e32 v0, v0
	v_add_f32_e32 v5, v5, v2
	v_add_f32_e32 v2, 0, v2
	v_add_f32_e32 v5, v4, v5
	v_add_f32_e32 v5, v0, v5
	v_div_scale_f32 v6, s[8:9], v5, v5, 1.0
	v_cndmask_b32_e64 v2, v2, 0, s[6:7]
	v_rcp_f32_e32 v8, v6
	v_readlane_b32 s6, v255, 20
	v_add_f32_e32 v4, v4, v2
	v_readlane_b32 s7, v255, 21
	v_div_scale_f32 v7, vcc, 1.0, v5, 1.0
	s_nop 0
	v_cndmask_b32_e64 v2, v2, v4, s[6:7]
	v_readlane_b32 s6, v255, 24
	v_add_f32_e32 v0, v0, v2
	v_readlane_b32 s7, v255, 25
	s_nop 1
	v_cndmask_b32_e64 v0, v2, v0, s[6:7]
	v_fma_f32 v2, -v6, v8, 1.0
	v_fmac_f32_e32 v8, v2, v8
	v_mul_f32_e32 v2, v7, v8
	v_fma_f32 v4, -v6, v2, v7
	v_fmac_f32_e32 v2, v4, v8
	v_fma_f32 v4, -v6, v2, v7
	v_div_fmas_f32 v2, v4, v8, v2
	v_div_fixup_f32 v2, v2, v5, 1.0
	v_mul_f32_e32 v0, v2, v0
	v_add_u32_e32 v2, 0x12000, v3
	ds_write_b32 v2, v0

; #define LAS __attribute__((address_space(3)))
; __device__ __forceinline__ void hg_item_C(const Params& p, int l, int seg, int h, LAS float* sm, int tid, int lane, int wave) {
;     ...
;     for (int i = tid; i < (L_SB - L_KT); i += 512) ((LAS unsigned*)(sm + L_KT))[i] = 0u;
.Lmy_hgc_staged:
	s_movk_i32 s0, 0x1040
	v_cmp_gt_i32_e32 vcc, s0, v54
	s_and_saveexec_b64 s[0:1], vcc
	s_cbranch_execz .LBB0_415
	v_readlane_b32 s2, v253, 61
	v_add_u32_e32 v0, 0xfffffe00, v54
	s_mov_b64 s[8:9], 0
	v_lshl_add_u32 v2, v54, 2, s2

;     __device__ __forceinline__ const float* in(int i) const { return (const float*)(const __attribute__((address_space(1))) float*)ld(i); }
; __device__ __forceinline__ void lds_barrier() { asm volatile("s_waitcnt lgkmcnt(0)" ::: "memory"); __builtin_amdgcn_s_barrier(); asm volatile("" ::: "memory"); }
; template <bool HG>
; __device__ __forceinline__ void diag_item_A(const Params& p, int l, int seg, int h, LAS float* sm, int tid, int lane, int wave) {
;     ...
;     lds_barrier();
;     if (HG) {
;         if (tid < 128) {
;             const float* lg = p.in(23) + h * 128 + tid;
;             const float x0 = lg[0], x1 = lg[512], x2 = lg[1024], x3 = lg[1536];
;             const float m = fmaxf(fmaxf(x0, x1), fmaxf(x2, x3));
;             const float e0 = __expf(x0 - m), e1 = __expf(x1 - m), e2 = __expf(x2 - m), e3 = __expf(x3 - m);
;             const float inv = 1.0f / (e0 + e1 + e2 + e3);
;             float lb = 0.f;
;             if (l >= 1) lb += e1; if (l >= 2) lb += e2; if (l >= 3) lb += e3;
;             sm[L_LB2 + tid] = lb * inv;
;         }
.LBB0_711:
	s_and_b64 vcc, exec, s[0:1]
	s_cbranch_vccz .LBB0_721
	s_waitcnt lgkmcnt(0)
	s_barrier
	s_movk_i32 s0, 0x80
	s_waitcnt lgkmcnt(0)
	v_readfirstlane_b32 s14, v32
	v_readfirstlane_b32 s15, v33
	v_cmp_gt_i32_e64 s[8:9], s0, v30
	v_ashrrev_i32_e32 v31, 31, v30
	s_waitcnt vmcnt(1)
	v_lshl_add_u32 v24, v30, 2, 0
	s_cmpk_gt_u32 s18, 0x3ff
	s_cbranch_scc1 .Lmy_hga_staged
	s_and_saveexec_b64 s[0:1], s[8:9]
	s_cbranch_execz .LBB0_714
	v_readlane_b32 s2, v253, 60
	s_lshl_b32 s12, s30, 9
	s_nop 0
	v_mov_b32_e32 v0, s2
	ds_read_b64 v[2:3], v0
	s_movk_i32 s2, 0x1000
	s_waitcnt lgkmcnt(0)
	v_readfirstlane_b32 s10, v2
	v_readfirstlane_b32 s11, v3
	s_add_u32 s10, s10, s12
	s_addc_u32 s11, s11, 0
	v_lshl_add_u64 v[2:3], v[30:31], 2, s[10:11]
	global_load_dword v0, v[2:3], off
	global_load_dword v4, v[2:3], off offset:2048
	v_add_co_u32_e32 v2, vcc, s2, v2
	s_nop 1
	v_addc_co_u32_e32 v3, vcc, 0, v3, vcc
	global_load_dword v5, v[2:3], off
	s_nop 0
	global_load_dword v2, v[2:3], off offset:2048
	s_waitcnt vmcnt(1)
	v_max_f32_e32 v6, v5, v5
	s_waitcnt vmcnt(0)
	v_max_f32_e32 v3, v2, v2
	v_max_f32_e32 v3, v6, v3
	v_max3_f32 v3, v0, v4, v3
	v_sub_f32_e32 v0, v0, v3
	v_sub_f32_e32 v4, v4, v3
	v_mul_f32_e32 v0, 0x3fb8aa3b, v0
	v_mul_f32_e32 v4, 0x3fb8aa3b, v4
	v_sub_f32_e32 v5, v5, v3
	v_exp_f32_e32 v0, v0
	v_exp_f32_e32 v4, v4
	v_mul_f32_e32 v5, 0x3fb8aa3b, v5
	v_sub_f32_e32 v2, v2, v3
	v_exp_f32_e32 v5, v5
	v_mul_f32_e32 v2, 0x3fb8aa3b, v2
	v_exp_f32_e32 v2, v2
	v_add_f32_e32 v0, v0, v4
	v_add_f32_e32 v0, v5, v0
	v_add_f32_e32 v0, v2, v0
	v_div_scale_f32 v3, s[10:11], v0, v0, 1.0
	v_rcp_f32_e32 v6, v3
	s_nop 0
	v_fma_f32 v7, -v3, v6, 1.0
	v_fmac_f32_e32 v6, v7, v6
	v_div_scale_f32 v7, vcc, 1.0, v0, 1.0
	v_mul_f32_e32 v8, v7, v6
	v_fma_f32 v9, -v3, v8, v7
	v_fmac_f32_e32 v8, v9, v6
	v_fma_f32 v3, -v3, v8, v7
	v_div_fmas_f32 v3, v3, v6, v8
	v_div_fixup_f32 v0, v3, v0, 1.0
	v_add_f32_e32 v3, 0, v4
	v_cndmask_b32_e64 v3, v3, 0, s[16:17]
	v_add_f32_e32 v4, v5, v3
	v_cndmask_b32_e64 v3, v3, v4, s[4:5]
	v_add_f32_e32 v2, v2, v3
	v_cndmask_b32_e64 v2, v3, v2, s[6:7]
	v_mul_f32_e32 v0, v0, v2
	v_add_u32_e32 v2, 0x12000, v24
	ds_write_b32 v2, v0

; #define LAS __attribute__((address_space(3)))
; template <bool HG>
; __device__ __forceinline__ void diag_item_A(const Params& p, int l, int seg, int h, LAS float* sm, int tid, int lane, int wave) {
;     ...
;     for (int i = tid; i < (L_VT - L_KT) + V * TP / 2; i += 512) ((LAS unsigned*)(sm + L_KT))[i] = 0u;
.Lmy_hga_staged:
	s_movk_i32 s0, 0xf00
	v_cmp_gt_i32_e32 vcc, s0, v30
	s_and_saveexec_b64 s[0:1], vcc
	s_cbranch_execz .LBB0_717
	s_add_i32 s10, 0, 0x14000
	v_add_u32_e32 v0, 0xfffffe00, v30
	v_lshl_add_u32 v2, v30, 2, s10
	s_mov_b64 s[10:11], 0
